# v70 + hand-written LN1 phase (wave per token, next token's row and modulation loads double-buffered, DPP wave sums)
# baseline (speedup 1.0000x reference)
.LBB1_70:
	s_and_b64 vcc, exec, s[30:31]
	s_cbranch_vccz .LBB1_75
	s_mov_b64 exec, -1
	s_mov_b64 s[30:31], -1
	v_lshrrev_b32_e32 v146, 6, v162
	v_readlane_b32 s2, v242, 0
	v_readlane_b32 s59, v241, 24
	v_readfirstlane_b32 s12, v146
	s_lshl_b32 s2, s2, 2
	s_add_u32 s54, s2, s12
	s_load_dwordx2 s[94:95], s[0:1], 0xc8
	v_lshlrev_b32_e32 v160, 6, v168
	v_lshlrev_b32_e32 v161, 5, v168
	v_readlane_b32 s40, v240, 12
	v_readlane_b32 s41, v240, 13
	v_readlane_b32 s42, v240, 14
	v_readlane_b32 s43, v240, 15
	s_nop 3
	s_sub_u32 s40, s40, 0x1000
	s_subb_u32 s41, s41, 0
	s_sub_u32 s42, s42, 0x1000
	s_subb_u32 s43, s43, 0
	s_waitcnt lgkmcnt(0)
	global_load_dwordx4 v[80:83], v160, s[40:41] offset:0
	global_load_dwordx4 v[84:87], v160, s[40:41] offset:16
	global_load_dwordx4 v[88:91], v160, s[40:41] offset:32
	global_load_dwordx4 v[92:95], v160, s[40:41] offset:48
	global_load_dwordx4 v[96:99], v160, s[42:43] offset:0
	global_load_dwordx4 v[100:103], v160, s[42:43] offset:16
	global_load_dwordx4 v[104:107], v160, s[42:43] offset:32
	global_load_dwordx4 v[108:111], v160, s[42:43] offset:48
	s_cmp_lt_u32 s54, 0x4200
	s_cbranch_scc0 .Lln1_done
	s_min_u32 s15, s54, 0x41ff
	s_lshl_b32 s50, s15, 12
	s_add_u32 s52, s72, s50
	s_addc_u32 s53, s73, 0
	global_load_dwordx4 v[48:51], v160, s[52:53] offset:0
	global_load_dwordx4 v[52:55], v160, s[52:53] offset:16
	global_load_dwordx4 v[56:59], v160, s[52:53] offset:32
	global_load_dwordx4 v[60:63], v160, s[52:53] offset:48
	s_cmp_lt_u32 s15, 0x2000
	s_cselect_b32 s14, 0, 1
	s_cmp_lt_u32 s15, 0x4000
	s_cselect_b32 s14, s14, 2
	s_add_u32 s16, s14, s27
	s_mul_i32 s16, s16, 0x6000
	s_add_u32 s16, s16, 0x3000
	s_add_u32 s46, s94, s16
	s_addc_u32 s47, s95, 0
	global_load_dwordx4 v[112:115], v160, s[46:47] offset:0
	global_load_dwordx4 v[116:119], v160, s[46:47] offset:16
	global_load_dwordx4 v[120:123], v160, s[46:47] offset:32
	global_load_dwordx4 v[124:127], v160, s[46:47] offset:48
	s_add_u32 s46, s46, 0x1000
	s_addc_u32 s47, s47, 0
	global_load_dwordx4 v[130:133], v160, s[46:47] offset:0
	global_load_dwordx4 v[134:137], v160, s[46:47] offset:16
	global_load_dwordx4 v[138:141], v160, s[46:47] offset:32
	global_load_dwordx4 v[142:145], v160, s[46:47] offset:48
.Lln1_tok:
	s_mov_b32 s2, s54
	s_add_u32 s99, s54, s59
	s_min_u32 s15, s99, 0x41ff
	s_lshl_b32 s50, s15, 12
	s_add_u32 s52, s72, s50
	s_addc_u32 s53, s73, 0
	global_load_dwordx4 v[0:3], v160, s[52:53] offset:0
	global_load_dwordx4 v[4:7], v160, s[52:53] offset:16
	global_load_dwordx4 v[8:11], v160, s[52:53] offset:32
	global_load_dwordx4 v[12:15], v160, s[52:53] offset:48
	s_cmp_lt_u32 s15, 0x2000
	s_cselect_b32 s14, 0, 1
	s_cmp_lt_u32 s15, 0x4000
	s_cselect_b32 s14, s14, 2
	s_add_u32 s16, s14, s27
	s_mul_i32 s16, s16, 0x6000
	s_add_u32 s16, s16, 0x3000
	s_add_u32 s46, s94, s16
	s_addc_u32 s47, s95, 0
	global_load_dwordx4 v[16:19], v160, s[46:47] offset:0
	global_load_dwordx4 v[20:23], v160, s[46:47] offset:16
	global_load_dwordx4 v[24:27], v160, s[46:47] offset:32
	global_load_dwordx4 v[28:31], v160, s[46:47] offset:48
	s_add_u32 s46, s46, 0x1000
	s_addc_u32 s47, s47, 0
	global_load_dwordx4 v[32:35], v160, s[46:47] offset:0
	global_load_dwordx4 v[36:39], v160, s[46:47] offset:16
	global_load_dwordx4 v[40:43], v160, s[46:47] offset:32
	global_load_dwordx4 v[44:47], v160, s[46:47] offset:48
	s_waitcnt vmcnt(12)
	v_add_f32_e32 v146, v48, v49
	v_add_f32_e32 v146, v146, v50
	v_add_f32_e32 v146, v146, v51
	v_add_f32_e32 v146, v146, v52
	v_add_f32_e32 v146, v146, v53
	v_add_f32_e32 v146, v146, v54
	v_add_f32_e32 v146, v146, v55
	v_add_f32_e32 v146, v146, v56
	v_add_f32_e32 v146, v146, v57
	v_add_f32_e32 v146, v146, v58
	v_add_f32_e32 v146, v146, v59
	v_add_f32_e32 v146, v146, v60
	v_add_f32_e32 v146, v146, v61
	v_add_f32_e32 v146, v146, v62
	v_add_f32_e32 v146, v146, v63
	s_nop 1
	v_add_f32_dpp v146, v146, v146 quad_perm:[1,0,3,2] row_mask:0xf bank_mask:0xf
	s_nop 1
	v_add_f32_dpp v146, v146, v146 quad_perm:[2,3,0,1] row_mask:0xf bank_mask:0xf
	s_nop 1
	v_add_f32_dpp v146, v146, v146 row_half_mirror row_mask:0xf bank_mask:0xf
	s_nop 1
	v_add_f32_dpp v146, v146, v146 row_mirror row_mask:0xf bank_mask:0xf
	s_nop 1
	v_readlane_b32 s8, v146, 0
	v_readlane_b32 s9, v146, 16
	v_readlane_b32 s10, v146, 32
	v_readlane_b32 s11, v146, 48
	s_nop 1
	v_mov_b32_e32 v147, s8
	v_add_f32_e32 v147, s9, v147
	v_add_f32_e32 v147, s10, v147
	v_add_f32_e32 v147, s11, v147
	v_mul_f32_e32 v147, 0x3a800000, v147
	v_sub_f32_e32 v48, v48, v147
	v_sub_f32_e32 v49, v49, v147
	v_sub_f32_e32 v50, v50, v147
	v_sub_f32_e32 v51, v51, v147
	v_sub_f32_e32 v52, v52, v147
	v_sub_f32_e32 v53, v53, v147
	v_sub_f32_e32 v54, v54, v147
	v_sub_f32_e32 v55, v55, v147
	v_sub_f32_e32 v56, v56, v147
	v_sub_f32_e32 v57, v57, v147
	v_sub_f32_e32 v58, v58, v147
	v_sub_f32_e32 v59, v59, v147
	v_sub_f32_e32 v60, v60, v147
	v_sub_f32_e32 v61, v61, v147
	v_sub_f32_e32 v62, v62, v147
	v_sub_f32_e32 v63, v63, v147
	v_mul_f32_e32 v146, v48, v48
	v_mul_f32_e32 v148, v49, v49
	v_add_f32_e32 v146, v146, v148
	v_mul_f32_e32 v148, v50, v50
	v_add_f32_e32 v146, v146, v148
	v_mul_f32_e32 v148, v51, v51
	v_add_f32_e32 v146, v146, v148
	v_mul_f32_e32 v148, v52, v52
	v_add_f32_e32 v146, v146, v148
	v_mul_f32_e32 v148, v53, v53
	v_add_f32_e32 v146, v146, v148
	v_mul_f32_e32 v148, v54, v54
	v_add_f32_e32 v146, v146, v148
	v_mul_f32_e32 v148, v55, v55
	v_add_f32_e32 v146, v146, v148
	v_mul_f32_e32 v148, v56, v56
	v_add_f32_e32 v146, v146, v148
	v_mul_f32_e32 v148, v57, v57
	v_add_f32_e32 v146, v146, v148
	v_mul_f32_e32 v148, v58, v58
	v_add_f32_e32 v146, v146, v148
	v_mul_f32_e32 v148, v59, v59
	v_add_f32_e32 v146, v146, v148
	v_mul_f32_e32 v148, v60, v60
	v_add_f32_e32 v146, v146, v148
	v_mul_f32_e32 v148, v61, v61
	v_add_f32_e32 v146, v146, v148
	v_mul_f32_e32 v148, v62, v62
	v_add_f32_e32 v146, v146, v148
	v_mul_f32_e32 v148, v63, v63
	v_add_f32_e32 v146, v146, v148
	s_nop 1
	v_add_f32_dpp v146, v146, v146 quad_perm:[1,0,3,2] row_mask:0xf bank_mask:0xf
	s_nop 1
	v_add_f32_dpp v146, v146, v146 quad_perm:[2,3,0,1] row_mask:0xf bank_mask:0xf
	s_nop 1
	v_add_f32_dpp v146, v146, v146 row_half_mirror row_mask:0xf bank_mask:0xf
	s_nop 1
	v_add_f32_dpp v146, v146, v146 row_mirror row_mask:0xf bank_mask:0xf
	s_nop 1
	v_readlane_b32 s8, v146, 0
	v_readlane_b32 s9, v146, 16
	v_readlane_b32 s10, v146, 32
	v_readlane_b32 s11, v146, 48
	s_nop 1
	v_mov_b32_e32 v147, s8
	v_add_f32_e32 v147, s9, v147
	v_add_f32_e32 v147, s10, v147
	v_add_f32_e32 v147, s11, v147
	v_fmamk_f32 v147, v147, 0x3a800000, v163
	s_mov_b32 s8, 0x800000
	v_cmp_gt_f32_e32 vcc, s8, v147
	v_mul_f32_e32 v148, 0x4b800000, v147
	s_nop 1
	v_cndmask_b32_e32 v147, v147, v148, vcc
	v_rsq_f32_e32 v147, v147
	s_nop 0
	v_mul_f32_e32 v148, 0x45800000, v147
	v_cndmask_b32_e32 v147, v147, v148, vcc
	v_mul_f32_e32 v48, v48, v147
	v_mul_f32_e32 v49, v49, v147
	v_mul_f32_e32 v50, v50, v147
	v_mul_f32_e32 v51, v51, v147
	v_mul_f32_e32 v52, v52, v147
	v_mul_f32_e32 v53, v53, v147
	v_mul_f32_e32 v54, v54, v147
	v_mul_f32_e32 v55, v55, v147
	v_mul_f32_e32 v56, v56, v147
	v_mul_f32_e32 v57, v57, v147
	v_mul_f32_e32 v58, v58, v147
	v_mul_f32_e32 v59, v59, v147
	v_mul_f32_e32 v60, v60, v147
	v_mul_f32_e32 v61, v61, v147
	v_mul_f32_e32 v62, v62, v147
	v_mul_f32_e32 v63, v63, v147
	v_fma_f32 v48, v80, v48, v96
	v_fma_f32 v49, v81, v49, v97
	v_fma_f32 v50, v82, v50, v98
	v_fma_f32 v51, v83, v51, v99
	v_fma_f32 v52, v84, v52, v100
	v_fma_f32 v53, v85, v53, v101
	v_fma_f32 v54, v86, v54, v102
	v_fma_f32 v55, v87, v55, v103
	v_fma_f32 v56, v88, v56, v104
	v_fma_f32 v57, v89, v57, v105
	v_fma_f32 v58, v90, v58, v106
	v_fma_f32 v59, v91, v59, v107
	v_fma_f32 v60, v92, v60, v108
	v_fma_f32 v61, v93, v61, v109
	v_fma_f32 v62, v94, v62, v110
	v_fma_f32 v63, v95, v63, v111
	s_lshl_b32 s50, s2, 12
	s_add_u32 s52, s70, s50
	s_addc_u32 s53, s71, 0
	global_store_dwordx4 v160, v[48:51], s[52:53] offset:0
	global_store_dwordx4 v160, v[52:55], s[52:53] offset:16
	global_store_dwordx4 v160, v[56:59], s[52:53] offset:32
	global_store_dwordx4 v160, v[60:63], s[52:53] offset:48
	v_add_f32_e32 v130, 1.0, v130
	v_add_f32_e32 v131, 1.0, v131
	v_add_f32_e32 v132, 1.0, v132
	v_add_f32_e32 v133, 1.0, v133
	v_add_f32_e32 v134, 1.0, v134
	v_add_f32_e32 v135, 1.0, v135
	v_add_f32_e32 v136, 1.0, v136
	v_add_f32_e32 v137, 1.0, v137
	v_add_f32_e32 v138, 1.0, v138
	v_add_f32_e32 v139, 1.0, v139
	v_add_f32_e32 v140, 1.0, v140
	v_add_f32_e32 v141, 1.0, v141
	v_add_f32_e32 v142, 1.0, v142
	v_add_f32_e32 v143, 1.0, v143
	v_add_f32_e32 v144, 1.0, v144
	v_add_f32_e32 v145, 1.0, v145
	v_fma_f32 v112, v48, v130, v112
	v_fma_f32 v113, v49, v131, v113
	v_fma_f32 v114, v50, v132, v114
	v_fma_f32 v115, v51, v133, v115
	v_fma_f32 v116, v52, v134, v116
	v_fma_f32 v117, v53, v135, v117
	v_fma_f32 v118, v54, v136, v118
	v_fma_f32 v119, v55, v137, v119
	v_fma_f32 v120, v56, v138, v120
	v_fma_f32 v121, v57, v139, v121
	v_fma_f32 v122, v58, v140, v122
	v_fma_f32 v123, v59, v141, v123
	v_fma_f32 v124, v60, v142, v124
	v_fma_f32 v125, v61, v143, v125
	v_fma_f32 v126, v62, v144, v126
	v_fma_f32 v127, v63, v145, v127
	v_cvt_pk_bf16_f32 v64, v112, v113
	v_cvt_pk_bf16_f32 v65, v114, v115
	v_cvt_pk_bf16_f32 v66, v116, v117
	v_cvt_pk_bf16_f32 v67, v118, v119
	v_cvt_pk_bf16_f32 v68, v120, v121
	v_cvt_pk_bf16_f32 v69, v122, v123
	v_cvt_pk_bf16_f32 v70, v124, v125
	v_cvt_pk_bf16_f32 v71, v126, v127
	s_lshl_b32 s50, s2, 11
	s_add_u32 s46, s74, s50
	s_addc_u32 s47, s75, 0
	global_store_dwordx4 v161, v[64:67], s[46:47]
	global_store_dwordx4 v161, v[68:71], s[46:47] offset:16
	s_nop 1
	s_mov_b32 s54, s99
	s_cmp_lt_u32 s54, 0x4200
	s_cbranch_scc0 .Lln1_end
	s_mov_b32 s2, s54
	s_add_u32 s99, s54, s59
	s_min_u32 s15, s99, 0x41ff
	s_lshl_b32 s50, s15, 12
	s_add_u32 s52, s72, s50
	s_addc_u32 s53, s73, 0
	global_load_dwordx4 v[48:51], v160, s[52:53] offset:0
	global_load_dwordx4 v[52:55], v160, s[52:53] offset:16
	global_load_dwordx4 v[56:59], v160, s[52:53] offset:32
	global_load_dwordx4 v[60:63], v160, s[52:53] offset:48
	s_cmp_lt_u32 s15, 0x2000
	s_cselect_b32 s14, 0, 1
	s_cmp_lt_u32 s15, 0x4000
	s_cselect_b32 s14, s14, 2
	s_add_u32 s16, s14, s27
	s_mul_i32 s16, s16, 0x6000
	s_add_u32 s16, s16, 0x3000
	s_add_u32 s46, s94, s16
	s_addc_u32 s47, s95, 0
	global_load_dwordx4 v[112:115], v160, s[46:47] offset:0
	global_load_dwordx4 v[116:119], v160, s[46:47] offset:16
	global_load_dwordx4 v[120:123], v160, s[46:47] offset:32
	global_load_dwordx4 v[124:127], v160, s[46:47] offset:48
	s_add_u32 s46, s46, 0x1000
	s_addc_u32 s47, s47, 0
	global_load_dwordx4 v[130:133], v160, s[46:47] offset:0
	global_load_dwordx4 v[134:137], v160, s[46:47] offset:16
	global_load_dwordx4 v[138:141], v160, s[46:47] offset:32
	global_load_dwordx4 v[142:145], v160, s[46:47] offset:48
	s_waitcnt vmcnt(12)
	v_add_f32_e32 v146, v0, v1
	v_add_f32_e32 v146, v146, v2
	v_add_f32_e32 v146, v146, v3
	v_add_f32_e32 v146, v146, v4
	v_add_f32_e32 v146, v146, v5
	v_add_f32_e32 v146, v146, v6
	v_add_f32_e32 v146, v146, v7
	v_add_f32_e32 v146, v146, v8
	v_add_f32_e32 v146, v146, v9
	v_add_f32_e32 v146, v146, v10
	v_add_f32_e32 v146, v146, v11
	v_add_f32_e32 v146, v146, v12
	v_add_f32_e32 v146, v146, v13
	v_add_f32_e32 v146, v146, v14
	v_add_f32_e32 v146, v146, v15
	s_nop 1
	v_add_f32_dpp v146, v146, v146 quad_perm:[1,0,3,2] row_mask:0xf bank_mask:0xf
	s_nop 1
	v_add_f32_dpp v146, v146, v146 quad_perm:[2,3,0,1] row_mask:0xf bank_mask:0xf
	s_nop 1
	v_add_f32_dpp v146, v146, v146 row_half_mirror row_mask:0xf bank_mask:0xf
	s_nop 1
	v_add_f32_dpp v146, v146, v146 row_mirror row_mask:0xf bank_mask:0xf
	s_nop 1
	v_readlane_b32 s8, v146, 0
	v_readlane_b32 s9, v146, 16
	v_readlane_b32 s10, v146, 32
	v_readlane_b32 s11, v146, 48
	s_nop 1
	v_mov_b32_e32 v147, s8
	v_add_f32_e32 v147, s9, v147
	v_add_f32_e32 v147, s10, v147
	v_add_f32_e32 v147, s11, v147
	v_mul_f32_e32 v147, 0x3a800000, v147
	v_sub_f32_e32 v0, v0, v147
	v_sub_f32_e32 v1, v1, v147
	v_sub_f32_e32 v2, v2, v147
	v_sub_f32_e32 v3, v3, v147
	v_sub_f32_e32 v4, v4, v147
	v_sub_f32_e32 v5, v5, v147
	v_sub_f32_e32 v6, v6, v147
	v_sub_f32_e32 v7, v7, v147
	v_sub_f32_e32 v8, v8, v147
	v_sub_f32_e32 v9, v9, v147
	v_sub_f32_e32 v10, v10, v147
	v_sub_f32_e32 v11, v11, v147
	v_sub_f32_e32 v12, v12, v147
	v_sub_f32_e32 v13, v13, v147
	v_sub_f32_e32 v14, v14, v147
	v_sub_f32_e32 v15, v15, v147
	v_mul_f32_e32 v146, v0, v0
	v_mul_f32_e32 v148, v1, v1
	v_add_f32_e32 v146, v146, v148
	v_mul_f32_e32 v148, v2, v2
	v_add_f32_e32 v146, v146, v148
	v_mul_f32_e32 v148, v3, v3
	v_add_f32_e32 v146, v146, v148
	v_mul_f32_e32 v148, v4, v4
	v_add_f32_e32 v146, v146, v148
	v_mul_f32_e32 v148, v5, v5
	v_add_f32_e32 v146, v146, v148
	v_mul_f32_e32 v148, v6, v6
	v_add_f32_e32 v146, v146, v148
	v_mul_f32_e32 v148, v7, v7
	v_add_f32_e32 v146, v146, v148
	v_mul_f32_e32 v148, v8, v8
	v_add_f32_e32 v146, v146, v148
	v_mul_f32_e32 v148, v9, v9
	v_add_f32_e32 v146, v146, v148
	v_mul_f32_e32 v148, v10, v10
	v_add_f32_e32 v146, v146, v148
	v_mul_f32_e32 v148, v11, v11
	v_add_f32_e32 v146, v146, v148
	v_mul_f32_e32 v148, v12, v12
	v_add_f32_e32 v146, v146, v148
	v_mul_f32_e32 v148, v13, v13
	v_add_f32_e32 v146, v146, v148
	v_mul_f32_e32 v148, v14, v14
	v_add_f32_e32 v146, v146, v148
	v_mul_f32_e32 v148, v15, v15
	v_add_f32_e32 v146, v146, v148
	s_nop 1
	v_add_f32_dpp v146, v146, v146 quad_perm:[1,0,3,2] row_mask:0xf bank_mask:0xf
	s_nop 1
	v_add_f32_dpp v146, v146, v146 quad_perm:[2,3,0,1] row_mask:0xf bank_mask:0xf
	s_nop 1
	v_add_f32_dpp v146, v146, v146 row_half_mirror row_mask:0xf bank_mask:0xf
	s_nop 1
	v_add_f32_dpp v146, v146, v146 row_mirror row_mask:0xf bank_mask:0xf
	s_nop 1
	v_readlane_b32 s8, v146, 0
	v_readlane_b32 s9, v146, 16
	v_readlane_b32 s10, v146, 32
	v_readlane_b32 s11, v146, 48
	s_nop 1
	v_mov_b32_e32 v147, s8
	v_add_f32_e32 v147, s9, v147
	v_add_f32_e32 v147, s10, v147
	v_add_f32_e32 v147, s11, v147
	v_fmamk_f32 v147, v147, 0x3a800000, v163
	s_mov_b32 s8, 0x800000
	v_cmp_gt_f32_e32 vcc, s8, v147
	v_mul_f32_e32 v148, 0x4b800000, v147
	s_nop 1
	v_cndmask_b32_e32 v147, v147, v148, vcc
	v_rsq_f32_e32 v147, v147
	s_nop 0
	v_mul_f32_e32 v148, 0x45800000, v147
	v_cndmask_b32_e32 v147, v147, v148, vcc
	v_mul_f32_e32 v0, v0, v147
	v_mul_f32_e32 v1, v1, v147
	v_mul_f32_e32 v2, v2, v147
	v_mul_f32_e32 v3, v3, v147
	v_mul_f32_e32 v4, v4, v147
	v_mul_f32_e32 v5, v5, v147
	v_mul_f32_e32 v6, v6, v147
	v_mul_f32_e32 v7, v7, v147
	v_mul_f32_e32 v8, v8, v147
	v_mul_f32_e32 v9, v9, v147
	v_mul_f32_e32 v10, v10, v147
	v_mul_f32_e32 v11, v11, v147
	v_mul_f32_e32 v12, v12, v147
	v_mul_f32_e32 v13, v13, v147
	v_mul_f32_e32 v14, v14, v147
	v_mul_f32_e32 v15, v15, v147
	v_fma_f32 v0, v80, v0, v96
	v_fma_f32 v1, v81, v1, v97
	v_fma_f32 v2, v82, v2, v98
	v_fma_f32 v3, v83, v3, v99
	v_fma_f32 v4, v84, v4, v100
	v_fma_f32 v5, v85, v5, v101
	v_fma_f32 v6, v86, v6, v102
	v_fma_f32 v7, v87, v7, v103
	v_fma_f32 v8, v88, v8, v104
	v_fma_f32 v9, v89, v9, v105
	v_fma_f32 v10, v90, v10, v106
	v_fma_f32 v11, v91, v11, v107
	v_fma_f32 v12, v92, v12, v108
	v_fma_f32 v13, v93, v13, v109
	v_fma_f32 v14, v94, v14, v110
	v_fma_f32 v15, v95, v15, v111
	s_lshl_b32 s50, s2, 12
	s_add_u32 s52, s70, s50
	s_addc_u32 s53, s71, 0
	global_store_dwordx4 v160, v[0:3], s[52:53] offset:0
	global_store_dwordx4 v160, v[4:7], s[52:53] offset:16
	global_store_dwordx4 v160, v[8:11], s[52:53] offset:32
	global_store_dwordx4 v160, v[12:15], s[52:53] offset:48
	v_add_f32_e32 v32, 1.0, v32
	v_add_f32_e32 v33, 1.0, v33
	v_add_f32_e32 v34, 1.0, v34
	v_add_f32_e32 v35, 1.0, v35
	v_add_f32_e32 v36, 1.0, v36
	v_add_f32_e32 v37, 1.0, v37
	v_add_f32_e32 v38, 1.0, v38
	v_add_f32_e32 v39, 1.0, v39
	v_add_f32_e32 v40, 1.0, v40
	v_add_f32_e32 v41, 1.0, v41
	v_add_f32_e32 v42, 1.0, v42
	v_add_f32_e32 v43, 1.0, v43
	v_add_f32_e32 v44, 1.0, v44
	v_add_f32_e32 v45, 1.0, v45
	v_add_f32_e32 v46, 1.0, v46
	v_add_f32_e32 v47, 1.0, v47
	v_fma_f32 v16, v0, v32, v16
	v_fma_f32 v17, v1, v33, v17
	v_fma_f32 v18, v2, v34, v18
	v_fma_f32 v19, v3, v35, v19
	v_fma_f32 v20, v4, v36, v20
	v_fma_f32 v21, v5, v37, v21
	v_fma_f32 v22, v6, v38, v22
	v_fma_f32 v23, v7, v39, v23
	v_fma_f32 v24, v8, v40, v24
	v_fma_f32 v25, v9, v41, v25
	v_fma_f32 v26, v10, v42, v26
	v_fma_f32 v27, v11, v43, v27
	v_fma_f32 v28, v12, v44, v28
	v_fma_f32 v29, v13, v45, v29
	v_fma_f32 v30, v14, v46, v30
	v_fma_f32 v31, v15, v47, v31
	v_cvt_pk_bf16_f32 v64, v16, v17
	v_cvt_pk_bf16_f32 v65, v18, v19
	v_cvt_pk_bf16_f32 v66, v20, v21
	v_cvt_pk_bf16_f32 v67, v22, v23
	v_cvt_pk_bf16_f32 v68, v24, v25
	v_cvt_pk_bf16_f32 v69, v26, v27
	v_cvt_pk_bf16_f32 v70, v28, v29
	v_cvt_pk_bf16_f32 v71, v30, v31
	s_lshl_b32 s50, s2, 11
	s_add_u32 s46, s74, s50
	s_addc_u32 s47, s75, 0
	global_store_dwordx4 v161, v[64:67], s[46:47]
	global_store_dwordx4 v161, v[68:71], s[46:47] offset:16
	s_nop 1
	s_mov_b32 s54, s99
	s_cmp_lt_u32 s54, 0x4200
	s_cbranch_scc1 .Lln1_tok
.Lln1_end:
.Lln1_done:
	s_waitcnt vmcnt(0)
	s_mov_b64 exec, -1
